# v29: v26 + prompt attention epilogues store 16 bytes per lane (v_permlane32_swap pairs the two halves): half the stores
# speedup vs baseline: 1.0035x; 1.0035x over previous
; DI unsigned pk2(float lo, float hi) { f32x2 v = {lo, hi}; bfv2 b = __builtin_convertvector(v, bfv2); return __builtin_bit_cast(unsigned, b); }
; DI float frcp(float x) { return __builtin_amdgcn_rcpf(x); }
;     DI void ostore(int, int d, u32x2 w) const { if (!dry) *(u32x2*)(qo + d) = w; }
;     DI void ostore(int r, int d, u32x2 w) const { if (!dry) *(u32x2*)(proj + (size_t)(MP + b * 8 + (r & 7)) * NPJ + C_SQ + (kvh * 4 + (r >> 3)) * 64 + d) = w; }
;     DI void ostore(int, int d, u32x2 w) const { if (!dry) *(u32x2*)(qo + d) = w; }
;     DI void ostore(int r, int d, u32x2 w) const { if (r < 8 && !dry) *(u32x2*)(proj + (size_t)(MP + b * 8 + r) * NPJ + C_MQ + hd * 128 + d) = w; }
; template <class T> DI void attn_item(const T& t) {
;     ...
;     const float inv = frcp(l);
; #pragma unroll
;     for (int dd = 0; dd < D / 32; ++dd)
; #pragma unroll
;         for (int g = 0; g < 4; ++g) { u32x2 w; w.x = pk2(o[dd][4 * g] * inv, o[dd][4 * g + 1] * inv); w.y = pk2(o[dd][4 * g + 2] * inv, o[dd][4 * g + 3] * inv); t.ostore(r, 32 * dd + 8 * g + 4 * h, w); }
.LBB0_957:
	s_nop 7
	s_nop 7
	v_rcp_f32_e32 v4, v223
	v_lshlrev_b32_e32 v2, 2, v186
	v_lshl_add_u64 v[6:7], v[216:217], 0, v[2:3]
	v_pk_mul_f32 v[84:85], v[66:67], v[4:5] op_sel_hi:[1,0]
	v_pk_mul_f32 v[88:89], v[68:69], v[4:5] op_sel_hi:[1,0]
	v_pk_mul_f32 v[86:87], v[70:71], v[4:5] op_sel_hi:[1,0]
	v_pk_mul_f32 v[90:91], v[72:73], v[4:5] op_sel_hi:[1,0]
	v_cvt_pk_bf16_f32 v84, v84, v85
	v_cvt_pk_bf16_f32 v85, v88, v89
	v_cvt_pk_bf16_f32 v86, v86, v87
	v_cvt_pk_bf16_f32 v87, v90, v91
	s_nop 1
	v_permlane32_swap_b32 v84, v86
	v_permlane32_swap_b32 v85, v87
	global_store_dwordx4 v[6:7], v[84:87], off
	v_pk_mul_f32 v[92:93], v[74:75], v[4:5] op_sel_hi:[1,0]
	v_pk_mul_f32 v[88:89], v[76:77], v[4:5] op_sel_hi:[1,0]
	v_pk_mul_f32 v[94:95], v[78:79], v[4:5] op_sel_hi:[1,0]
	v_pk_mul_f32 v[90:91], v[80:81], v[4:5] op_sel_hi:[1,0]
	v_cvt_pk_bf16_f32 v92, v92, v93
	v_cvt_pk_bf16_f32 v93, v88, v89
	v_cvt_pk_bf16_f32 v94, v94, v95
	v_cvt_pk_bf16_f32 v95, v90, v91
	s_nop 1
	v_permlane32_swap_b32 v92, v94
	v_permlane32_swap_b32 v93, v95
	global_store_dwordx4 v[6:7], v[92:95], off offset:32
	v_pk_mul_f32 v[84:85], v[50:51], v[4:5] op_sel_hi:[1,0]
	v_pk_mul_f32 v[88:89], v[52:53], v[4:5] op_sel_hi:[1,0]
	v_pk_mul_f32 v[86:87], v[54:55], v[4:5] op_sel_hi:[1,0]
	v_pk_mul_f32 v[90:91], v[56:57], v[4:5] op_sel_hi:[1,0]
	v_cvt_pk_bf16_f32 v84, v84, v85
	v_cvt_pk_bf16_f32 v85, v88, v89
	v_cvt_pk_bf16_f32 v86, v86, v87
	v_cvt_pk_bf16_f32 v87, v90, v91
	s_nop 1
	v_permlane32_swap_b32 v84, v86
	v_permlane32_swap_b32 v85, v87
	global_store_dwordx4 v[6:7], v[84:87], off offset:64
	v_pk_mul_f32 v[92:93], v[58:59], v[4:5] op_sel_hi:[1,0]
	v_pk_mul_f32 v[88:89], v[60:61], v[4:5] op_sel_hi:[1,0]
	v_pk_mul_f32 v[94:95], v[62:63], v[4:5] op_sel_hi:[1,0]
	v_pk_mul_f32 v[90:91], v[64:65], v[4:5] op_sel_hi:[1,0]
	v_cvt_pk_bf16_f32 v92, v92, v93
	v_cvt_pk_bf16_f32 v93, v88, v89
	v_cvt_pk_bf16_f32 v94, v94, v95
	v_cvt_pk_bf16_f32 v95, v90, v91
	s_nop 1
	v_permlane32_swap_b32 v92, v94
	v_permlane32_swap_b32 v93, v95
	global_store_dwordx4 v[6:7], v[92:95], off offset:96
	v_pk_mul_f32 v[84:85], v[34:35], v[4:5] op_sel_hi:[1,0]
	v_pk_mul_f32 v[88:89], v[36:37], v[4:5] op_sel_hi:[1,0]
	v_pk_mul_f32 v[86:87], v[38:39], v[4:5] op_sel_hi:[1,0]
	v_pk_mul_f32 v[90:91], v[40:41], v[4:5] op_sel_hi:[1,0]
	v_cvt_pk_bf16_f32 v84, v84, v85
	v_cvt_pk_bf16_f32 v85, v88, v89
	v_cvt_pk_bf16_f32 v86, v86, v87
	v_cvt_pk_bf16_f32 v87, v90, v91
	s_nop 1
	v_permlane32_swap_b32 v84, v86
	v_permlane32_swap_b32 v85, v87
	global_store_dwordx4 v[6:7], v[84:87], off offset:128
	v_pk_mul_f32 v[92:93], v[42:43], v[4:5] op_sel_hi:[1,0]
	v_pk_mul_f32 v[88:89], v[44:45], v[4:5] op_sel_hi:[1,0]
	v_pk_mul_f32 v[94:95], v[46:47], v[4:5] op_sel_hi:[1,0]
	v_pk_mul_f32 v[90:91], v[48:49], v[4:5] op_sel_hi:[1,0]
	v_cvt_pk_bf16_f32 v92, v92, v93
	v_cvt_pk_bf16_f32 v93, v88, v89
	v_cvt_pk_bf16_f32 v94, v94, v95
	v_cvt_pk_bf16_f32 v95, v90, v91
	s_nop 1
	v_permlane32_swap_b32 v92, v94
	v_permlane32_swap_b32 v93, v95
	global_store_dwordx4 v[6:7], v[92:95], off offset:160
	v_pk_mul_f32 v[84:85], v[18:19], v[4:5] op_sel_hi:[1,0]
	v_pk_mul_f32 v[88:89], v[20:21], v[4:5] op_sel_hi:[1,0]
	v_pk_mul_f32 v[86:87], v[22:23], v[4:5] op_sel_hi:[1,0]
	v_pk_mul_f32 v[90:91], v[24:25], v[4:5] op_sel_hi:[1,0]
	v_cvt_pk_bf16_f32 v84, v84, v85
	v_cvt_pk_bf16_f32 v85, v88, v89
	v_cvt_pk_bf16_f32 v86, v86, v87
	v_cvt_pk_bf16_f32 v87, v90, v91
	s_nop 1
	v_permlane32_swap_b32 v84, v86
	v_permlane32_swap_b32 v85, v87
	global_store_dwordx4 v[6:7], v[84:87], off offset:192
	v_pk_mul_f32 v[92:93], v[26:27], v[4:5] op_sel_hi:[1,0]
	v_pk_mul_f32 v[88:89], v[28:29], v[4:5] op_sel_hi:[1,0]
	v_pk_mul_f32 v[94:95], v[30:31], v[4:5] op_sel_hi:[1,0]
	v_pk_mul_f32 v[90:91], v[32:33], v[4:5] op_sel_hi:[1,0]
	v_cvt_pk_bf16_f32 v92, v92, v93
	v_cvt_pk_bf16_f32 v93, v88, v89
	v_cvt_pk_bf16_f32 v94, v94, v95
	v_cvt_pk_bf16_f32 v95, v90, v91
	s_nop 1
	v_permlane32_swap_b32 v92, v94
	v_permlane32_swap_b32 v93, v95
	global_store_dwordx4 v[6:7], v[92:95], off offset:224

; DI unsigned pk2(float lo, float hi) { f32x2 v = {lo, hi}; bfv2 b = __builtin_convertvector(v, bfv2); return __builtin_bit_cast(unsigned, b); }
; DI float frcp(float x) { return __builtin_amdgcn_rcpf(x); }
;     DI void ostore(int, int d, u32x2 w) const { if (!dry) *(u32x2*)(qo + d) = w; }
;     DI void ostore(int r, int d, u32x2 w) const { if (!dry) *(u32x2*)(proj + (size_t)(MP + b * 8 + (r & 7)) * NPJ + C_SQ + (kvh * 4 + (r >> 3)) * 64 + d) = w; }
;     DI void ostore(int, int d, u32x2 w) const { if (!dry) *(u32x2*)(qo + d) = w; }
;     DI void ostore(int r, int d, u32x2 w) const { if (r < 8 && !dry) *(u32x2*)(proj + (size_t)(MP + b * 8 + r) * NPJ + C_MQ + hd * 128 + d) = w; }
; template <class T> DI void attn_item(const T& t) {
;     ...
;     const float inv = frcp(l);
; #pragma unroll
;     for (int dd = 0; dd < D / 32; ++dd)
; #pragma unroll
;         for (int g = 0; g < 4; ++g) { u32x2 w; w.x = pk2(o[dd][4 * g] * inv, o[dd][4 * g + 1] * inv); w.y = pk2(o[dd][4 * g + 2] * inv, o[dd][4 * g + 3] * inv); t.ostore(r, 32 * dd + 8 * g + 4 * h, w); }
.LBB0_979:
	s_nop 7
	s_nop 7
	v_rcp_f32_e32 v36, v125
	v_lshlrev_b32_e32 v38, 2, v186
	v_mov_b32_e32 v39, v3
	v_lshl_add_u64 v[38:39], v[100:101], 0, v[38:39]
	v_pk_mul_f32 v[40:41], v[20:21], v[36:37] op_sel_hi:[1,0]
	v_pk_mul_f32 v[44:45], v[22:23], v[36:37] op_sel_hi:[1,0]
	v_pk_mul_f32 v[42:43], v[24:25], v[36:37] op_sel_hi:[1,0]
	v_pk_mul_f32 v[46:47], v[26:27], v[36:37] op_sel_hi:[1,0]
	v_cvt_pk_bf16_f32 v40, v40, v41
	v_cvt_pk_bf16_f32 v41, v44, v45
	v_cvt_pk_bf16_f32 v42, v42, v43
	v_cvt_pk_bf16_f32 v43, v46, v47
	s_nop 1
	v_permlane32_swap_b32 v40, v42
	v_permlane32_swap_b32 v41, v43
	global_store_dwordx4 v[38:39], v[40:43], off
	v_pk_mul_f32 v[48:49], v[28:29], v[36:37] op_sel_hi:[1,0]
	v_pk_mul_f32 v[44:45], v[30:31], v[36:37] op_sel_hi:[1,0]
	v_pk_mul_f32 v[50:51], v[32:33], v[36:37] op_sel_hi:[1,0]
	v_pk_mul_f32 v[46:47], v[34:35], v[36:37] op_sel_hi:[1,0]
	v_cvt_pk_bf16_f32 v48, v48, v49
	v_cvt_pk_bf16_f32 v49, v44, v45
	v_cvt_pk_bf16_f32 v50, v50, v51
	v_cvt_pk_bf16_f32 v51, v46, v47
	s_nop 1
	v_permlane32_swap_b32 v48, v50
	v_permlane32_swap_b32 v49, v51
	global_store_dwordx4 v[38:39], v[48:51], off offset:32
	v_pk_mul_f32 v[40:41], v[4:5], v[36:37] op_sel_hi:[1,0]
	v_pk_mul_f32 v[44:45], v[6:7], v[36:37] op_sel_hi:[1,0]
	v_pk_mul_f32 v[42:43], v[8:9], v[36:37] op_sel_hi:[1,0]
	v_pk_mul_f32 v[46:47], v[10:11], v[36:37] op_sel_hi:[1,0]
	v_cvt_pk_bf16_f32 v40, v40, v41
	v_cvt_pk_bf16_f32 v41, v44, v45
	v_cvt_pk_bf16_f32 v42, v42, v43
	v_cvt_pk_bf16_f32 v43, v46, v47
	s_nop 1
	v_permlane32_swap_b32 v40, v42
	v_permlane32_swap_b32 v41, v43
	global_store_dwordx4 v[38:39], v[40:43], off offset:64
	v_pk_mul_f32 v[48:49], v[12:13], v[36:37] op_sel_hi:[1,0]
	v_pk_mul_f32 v[44:45], v[14:15], v[36:37] op_sel_hi:[1,0]
	v_pk_mul_f32 v[50:51], v[16:17], v[36:37] op_sel_hi:[1,0]
	v_pk_mul_f32 v[46:47], v[18:19], v[36:37] op_sel_hi:[1,0]
	v_cvt_pk_bf16_f32 v48, v48, v49
	v_cvt_pk_bf16_f32 v49, v44, v45
	v_cvt_pk_bf16_f32 v50, v50, v51
	v_cvt_pk_bf16_f32 v51, v46, v47
	s_nop 1
	v_permlane32_swap_b32 v48, v50
	v_permlane32_swap_b32 v49, v51
	global_store_dwordx4 v[38:39], v[48:51], off offset:96
	s_mov_b64 s[40:41], 0
